# strip start waits only for Q rows (vmcnt 8), not previous strip stores
# speedup vs baseline: 1.0019x; 1.0019x over previous
.LBB0_220:
	s_waitcnt vmcnt(0)
	v_readlane_b32 s0, v253, 49
	v_readlane_b32 s1, v253, 50
	s_andn2_b64 vcc, exec, s[0:1]
	v_readlane_b32 s14, v253, 60
	v_readlane_b32 s16, v253, 59
	s_cbranch_vccnz .LBB0_235

.LBB0_226:
	s_waitcnt vmcnt(8)
	v_mov_b32_e32 v2, v211
	s_movk_i32 s4, 0x110
	v_ashrrev_i32_e32 v228, 4, v2
	v_mul_lo_u32 v0, v228, s4
	v_lshlrev_b32_e32 v3, 4, v2
	v_add_u32_e32 v235, s28, v0
	v_and_b32_e32 v0, 0xf0, v3
	v_add_u32_e32 v0, v235, v0
	v_and_b32_e32 v230, 31, v2
	s_waitcnt vmcnt(8)
	ds_write_b128 v0, v[66:69]
	ds_write_b128 v0, v[70:73] offset:1088
	ds_write_b128 v0, v[78:81] offset:2176
	ds_write_b128 v0, v[74:77] offset:3264
	ds_write_b128 v0, v[86:89] offset:4352
	ds_write_b128 v0, v[82:85] offset:5440
	ds_write_b128 v0, v[94:97] offset:6528
	ds_write_b128 v0, v[90:93] offset:7616
	v_mov_b32_e32 v0, s28
	v_ashrrev_i32_e32 v4, 1, v2
	v_mad_u32_u24 v0, v230, s4, v0
	v_and_b32_e32 v4, -16, v4
	v_add_u32_e32 v236, v0, v4
	v_lshlrev_b32_e32 v233, 3, v2
	v_and_b32_e32 v0, 0xc0, v3
	v_lshlrev_b32_e32 v4, 1, v2
	s_waitcnt lgkmcnt(0)
	v_and_or_b32 v0, v233, 24, v0
	v_and_b32_e32 v4, 32, v4
	v_and_b32_e32 v5, 0x100, v233
	v_or3_b32 v0, v0, v4, v5
	s_ashr_i32 s4, s16, 1
	ds_read_b128 v[98:101], v236
	ds_read_b128 v[102:105], v236 offset:32
	ds_read_b128 v[106:109], v236 offset:64
	ds_read_b128 v[110:113], v236 offset:96
	ds_read_b128 v[114:117], v236 offset:128
	ds_read_b128 v[118:121], v236 offset:160
	ds_read_b128 v[122:125], v236 offset:192
	ds_read_b128 v[126:129], v236 offset:224
	v_add_u32_e32 v237, s28, v0
	s_and_b32 s17, s4, 0xffffff80
	v_and_b32_e32 v0, 15, v2
	s_movk_i32 s4, 0x2800
	v_lshlrev_b32_e32 v229, 3, v0
	v_mul_lo_u32 v234, v228, s4
	v_or_b32_e32 v4, v229, v234
	v_lshlrev_b32_e32 v238, 4, v0
	v_lshlrev_b32_e32 v0, 7, v2
	v_and_b32_e32 v0, 0x600, v0
	v_add_u32_e32 v4, s17, v4
	v_add_u32_e32 v5, s28, v0
	v_add_u32_e32 v0, 0x600, v4
	v_lshl_add_u64 v[190:191], v[0:1], 1, s[10:11]
	v_add_u32_e32 v0, 0xc00, v4
	v_lshl_add_u64 v[192:193], v[0:1], 1, s[10:11]
	v_lshlrev_b32_e32 v0, 2, v2
	s_xor_b64 s[8:9], s[0:1], -1
	s_and_b32 s0, s14, 0x1fe0
	v_ashrrev_i32_e32 v231, 5, v2
	s_waitcnt lgkmcnt(0)
	v_and_b32_e32 v0, 0xffffffc0, v0
	s_and_b32 s1, s14, 0x1fc0
	v_lshl_add_u32 v6, v228, 6, v5
	v_cmp_gt_u32_e64 s[38:39], 32, v2
	v_add_u32_e32 v5, v5, v0
	v_lshlrev_b32_e32 v0, 2, v231
	v_or_b32_e32 v2, s0, v230
	v_and_b32_e32 v4, 48, v238
	v_and_b32_e32 v3, 48, v3
	v_add_u32_e32 v201, 18, v0
	v_add_u32_e32 v200, 16, v0
	v_add_u32_e32 v203, 19, v0
	v_add_u32_e32 v202, 17, v0
	v_subrev_u32_e32 v239, s1, v2
	v_mov_b32_e32 v2, 0
	s_or_b32 s23, s1, 60
	v_add_u32_e32 v175, 27, v0
	v_or_b32_e32 v177, 2, v0
	v_or_b32_e32 v195, 3, v0
	v_or_b32_e32 v194, 1, v0
	v_add_u32_e32 v197, 10, v0
	v_add_u32_e32 v196, 8, v0
	v_add_u32_e32 v199, 11, v0
	v_add_u32_e32 v198, 9, v0
	v_add_u32_e32 v205, 24, v0
	v_add_u32_e32 v207, 25, v0
	v_add_u32_e32 v209, 26, v0
	v_mov_b32_e32 v204, v200
	v_mov_b32_e32 v206, v202
	v_mov_b32_e32 v208, v201
	v_mov_b32_e32 v210, v203
	v_mov_b32_e32 v240, 1.0
	v_add_u32_e32 v241, v6, v4
	v_add_u32_e32 v242, v5, v3
	v_mov_b32_e32 v3, v2
	v_mov_b32_e32 v4, v2
	v_mov_b32_e32 v5, v2
	v_mov_b32_e32 v6, v2
	v_mov_b32_e32 v7, v2
	v_mov_b32_e32 v8, v2
	v_mov_b32_e32 v9, v2
	v_mov_b32_e32 v10, v2
	v_mov_b32_e32 v11, v2
	v_mov_b32_e32 v12, v2
	v_mov_b32_e32 v13, v2
	v_mov_b32_e32 v14, v2
	v_mov_b32_e32 v15, v2
	v_mov_b32_e32 v16, v2
	v_mov_b32_e32 v17, v2
	v_mov_b32_e32 v18, v2
	v_mov_b32_e32 v19, v2
	v_mov_b32_e32 v20, v2
	v_mov_b32_e32 v21, v2
	v_mov_b32_e32 v22, v2
	v_mov_b32_e32 v23, v2
	v_mov_b32_e32 v24, v2
	v_mov_b32_e32 v25, v2
	v_mov_b32_e32 v26, v2
	v_mov_b32_e32 v27, v2
	v_mov_b32_e32 v28, v2
	v_mov_b32_e32 v29, v2
	v_mov_b32_e32 v30, v2
	v_mov_b32_e32 v31, v2
	v_mov_b32_e32 v32, v2
	v_mov_b32_e32 v33, v2
	v_mov_b32_e32 v34, v2
	v_mov_b32_e32 v35, v2
	v_mov_b32_e32 v36, v2
	v_mov_b32_e32 v37, v2
	v_mov_b32_e32 v38, v2
	v_mov_b32_e32 v39, v2
	v_mov_b32_e32 v40, v2
	v_mov_b32_e32 v41, v2
	v_mov_b32_e32 v42, v2
	v_mov_b32_e32 v43, v2
	v_mov_b32_e32 v44, v2
	v_mov_b32_e32 v45, v2
	v_mov_b32_e32 v46, v2
	v_mov_b32_e32 v47, v2
	v_mov_b32_e32 v48, v2
	v_mov_b32_e32 v49, v2
	v_mov_b32_e32 v50, v2
	v_mov_b32_e32 v51, v2
	v_mov_b32_e32 v52, v2
	v_mov_b32_e32 v53, v2
	v_mov_b32_e32 v54, v2
	v_mov_b32_e32 v55, v2
	v_mov_b32_e32 v56, v2
	v_mov_b32_e32 v57, v2
	v_mov_b32_e32 v58, v2
	v_mov_b32_e32 v59, v2
	v_mov_b32_e32 v60, v2
	v_mov_b32_e32 v61, v2
	v_mov_b32_e32 v62, v2
	v_mov_b32_e32 v63, v2
	v_mov_b32_e32 v64, v2
	v_mov_b32_e32 v65, v2

.LBB0_241:
	s_mul_hi_i32 s1, s0, 0x2aaaaaab
	s_lshr_b32 s6, s1, 31
	s_ashr_i32 s25, s1, 9
	s_add_i32 s25, s25, s6
	s_mul_i32 s1, s25, 0xc00
	s_sub_i32 s1, s0, s1
	s_ashr_i32 s14, s1, 8
	s_add_i32 s8, s0, 0xbff
	s_addk_i32 s0, 0xf400
	s_and_b32 s16, s1, 0xff
	s_cmpk_lt_u32 s0, 0xc00
	s_cselect_b64 s[6:7], -1, 0
	s_and_b64 s[0:1], s[6:7], exec
	s_cselect_b32 s17, 4, 16
	s_cselect_b32 s22, 2, 4
	s_cmpk_lt_u32 s8, 0x17ff
	s_cselect_b64 s[8:9], -1, 0
	s_and_b64 s[0:1], s[8:9], exec
	s_cselect_b32 s22, 0, s22
	s_cselect_b32 s19, 1, s17
	s_sub_i32 s1, 8, s22
	v_mov_b32_e32 v173, v211
	s_lshr_b32 s23, s16, s1
	s_movk_i32 s1, 0x110
	v_ashrrev_i32_e32 v177, 4, v173
	v_mul_lo_u32 v0, v177, s1
	s_waitcnt vmcnt(8)
	v_lshlrev_b32_e32 v2, 4, v173
	v_add_u32_e32 v168, s28, v0
	v_and_b32_e32 v0, 0xf0, v2
	v_add_u32_e32 v0, v168, v0
	v_and_b32_e32 v171, 31, v173
	s_waitcnt vmcnt(8)
	ds_write_b128 v0, v[66:69]
	ds_write_b128 v0, v[70:73] offset:1088
	ds_write_b128 v0, v[78:81] offset:2176
	ds_write_b128 v0, v[74:77] offset:3264
	ds_write_b128 v0, v[86:89] offset:4352
	ds_write_b128 v0, v[82:85] offset:5440
	ds_write_b128 v0, v[94:97] offset:6528
	ds_write_b128 v0, v[90:93] offset:7616
	v_mov_b32_e32 v0, s28
	v_ashrrev_i32_e32 v3, 1, v173
	s_waitcnt lgkmcnt(0)
	v_mad_u32_u24 v0, v171, s1, v0
	v_and_b32_e32 v3, -16, v3
	v_add_u32_e32 v166, v0, v3
	ds_read_b128 v[98:101], v166
	ds_read_b128 v[102:105], v166 offset:32
	ds_read_b128 v[106:109], v166 offset:64
	ds_read_b128 v[110:113], v166 offset:96
	ds_read_b128 v[114:117], v166 offset:128
	ds_read_b128 v[118:121], v166 offset:160
	ds_read_b128 v[122:125], v166 offset:192
	ds_read_b128 v[126:129], v166 offset:224
	s_lshr_b32 s0, 0x100, s22
	s_add_i32 s0, s0, -1
	s_and_b32 s0, s0, s16
	s_lshl_b32 s24, s0, 5
	s_add_i32 s1, s24, 0xffffff80
	s_waitcnt lgkmcnt(0)
	s_lshr_b32 s1, s1, 6
	s_cmp_gt_u32 s0, 3
	s_cselect_b32 s36, s1, 0
	s_lshr_b32 s37, s0, 1
	v_ashrrev_i32_e32 v172, 5, v173
	v_lshlrev_b32_e32 v190, 3, v173
	s_cmp_gt_u32 s36, s37
	v_lshlrev_b32_e32 v170, s22, v177
	v_and_b32_e32 v169, 15, v173
	v_cmp_gt_u32_e64 s[0:1], 32, v173
	v_lshl_add_u32 v175, v171, 2, s28
	s_cbranch_scc1 .LBB0_250
	v_and_b32_e32 v0, 0xc0, v2
	v_lshlrev_b32_e32 v3, 1, v173
	v_and_or_b32 v0, v190, 24, v0
	v_and_b32_e32 v3, 32, v3
	v_and_b32_e32 v4, 0x100, v190
	s_lshl_b32 s16, s14, 7
	v_or3_b32 v0, v0, v3, v4
	s_add_i32 s17, s16, 0x1800
	s_add_i32 s50, s16, 0x1e00
	s_movk_i32 s16, 0x2800
	v_add_u32_e32 v191, s28, v0
	v_mul_lo_u32 v0, v170, s16
	v_lshl_or_b32 v3, v169, 3, v0
	v_lshlrev_b32_e32 v0, 7, v173
	v_and_b32_e32 v0, 0x600, v0
	s_lshl_b32 s38, s19, 2
	v_add_u32_e32 v4, s28, v0
	v_add_u32_e32 v0, s17, v3
	s_and_b64 s[16:17], s[6:7], exec
	s_cselect_b32 s39, 48, 0xc0
	s_and_b64 s[16:17], s[8:9], exec
	s_cselect_b32 s39, 12, s39
	s_and_b64 s[16:17], s[6:7], exec
	s_movk_i32 s16, 0x50
	s_cselect_b32 s40, s16, 0x140
	s_and_b64 s[16:17], s[8:9], exec
	s_cselect_b32 s40, 20, s40
	s_and_b64 s[16:17], s[6:7], exec
	s_movk_i32 s16, 0x60
	s_cselect_b32 s41, s16, 0x180
	s_and_b64 s[16:17], s[8:9], exec
	s_cselect_b32 s41, 24, s41
	s_and_b64 s[16:17], s[6:7], exec
	s_movk_i32 s16, 0x70
	s_cselect_b32 s42, s16, 0x1c0
	s_and_b64 s[16:17], s[8:9], exec
	s_cselect_b32 s42, 28, s42
	s_and_b64 s[16:17], s[6:7], exec
	s_movk_i32 s16, 0x240
	s_cselect_b32 s43, 0x90, s16
	s_and_b64 s[16:17], s[8:9], exec
	s_cselect_b32 s43, 36, s43
	s_and_b64 s[16:17], s[6:7], exec
	s_movk_i32 s16, 0x280
	s_cselect_b32 s44, 0xa0, s16
	s_and_b64 s[16:17], s[8:9], exec
	s_cselect_b32 s44, 40, s44
	s_and_b64 s[16:17], s[6:7], exec
	s_movk_i32 s16, 0x2c0
	s_cselect_b32 s45, 0xb0, s16
	s_and_b64 s[16:17], s[8:9], exec
	s_cselect_b32 s45, 44, s45
	s_and_b64 s[16:17], s[6:7], exec
	s_movk_i32 s16, 0x300
	s_cselect_b32 s46, 0xc0, s16
	s_and_b64 s[16:17], s[8:9], exec
	s_cselect_b32 s46, 48, s46
	s_and_b64 s[16:17], s[6:7], exec
	s_movk_i32 s16, 0xd0
	s_cselect_b32 s47, s16, 0x340
	s_and_b64 s[16:17], s[8:9], exec
	s_cselect_b32 s47, 52, s47
	s_and_b64 s[16:17], s[6:7], exec
	s_movk_i32 s16, 0xe0
	s_cselect_b32 s48, s16, 0x380
	s_and_b64 s[16:17], s[8:9], exec
	s_cselect_b32 s48, 56, s48
	s_and_b64 s[16:17], s[6:7], exec
	v_lshl_add_u64 v[162:163], v[0:1], 1, s[10:11]
	s_movk_i32 s16, 0x3c0
	v_add_u32_e32 v0, s50, v3
	s_cselect_b32 s49, 0xf0, s16
	s_and_b64 s[16:17], s[8:9], exec
	v_lshl_add_u64 v[164:165], v[0:1], 1, s[10:11]
	v_lshlrev_b32_e32 v0, 2, v173
	s_cselect_b32 s49, 60, s49
	v_and_b32_e32 v0, 0xffffffc0, v0
	s_sub_i32 s16, s24, 59
	v_and_b32_e32 v19, 48, v2
	v_add_u32_e32 v20, v4, v0
	v_add_u32_e32 v0, s16, v171
	v_lshlrev_b32_e32 v2, 2, v172
	v_lshlrev_b32_e32 v192, 4, v169
	v_lshlrev_b32_e32 v18, 4, v172
	v_sub_u32_e32 v0, v0, v2
	s_lshl_b32 s52, s36, 6
	v_mov_b32_e32 v14, v1
	v_mov_b32_e32 v15, v1
	v_lshl_add_u32 v16, v177, 6, v4
	v_and_b32_e32 v17, 48, v192
	v_subrev_u32_e32 v193, s52, v0
	v_mov_b32_e32 v0, v1
	v_mov_b32_e32 v2, v1
	v_mov_b32_e32 v3, v1
	v_mov_b32_e32 v4, v1
	v_mov_b32_e32 v5, v1
	v_mov_b32_e32 v6, v1
	v_mov_b32_e32 v7, v1
	v_mov_b32_e32 v8, v1
	v_mov_b32_e32 v9, v1
	v_mov_b32_e32 v10, v1
	v_mov_b32_e32 v11, v1
	v_mov_b32_e32 v12, v1
	v_mov_b32_e32 v13, v1
	v_add_u32_e32 v195, s28, v18
	v_add_u32_e32 v196, v20, v19
	v_mov_b64_e32 v[64:65], v[14:15]
	v_mov_b64_e32 v[48:49], v[14:15]
	v_mov_b64_e32 v[32:33], v[14:15]
	v_add_u32_e32 v194, v16, v17
	v_mov_b64_e32 v[62:63], v[12:13]
	v_mov_b64_e32 v[60:61], v[10:11]
	v_mov_b64_e32 v[58:59], v[8:9]
	v_mov_b64_e32 v[56:57], v[6:7]
	v_mov_b64_e32 v[54:55], v[4:5]
	v_mov_b64_e32 v[52:53], v[2:3]
	v_mov_b64_e32 v[50:51], v[0:1]
	v_mov_b64_e32 v[46:47], v[12:13]
	v_mov_b64_e32 v[44:45], v[10:11]
	v_mov_b64_e32 v[42:43], v[8:9]
	v_mov_b64_e32 v[40:41], v[6:7]
	v_mov_b64_e32 v[38:39], v[4:5]
	v_mov_b64_e32 v[36:37], v[2:3]
	v_mov_b64_e32 v[34:35], v[0:1]
	v_mov_b64_e32 v[30:31], v[12:13]
	v_mov_b64_e32 v[28:29], v[10:11]
	v_mov_b64_e32 v[26:27], v[8:9]
	v_mov_b64_e32 v[24:25], v[6:7]
	v_mov_b64_e32 v[22:23], v[4:5]
	v_mov_b64_e32 v[20:21], v[2:3]
	v_mov_b64_e32 v[18:19], v[0:1]
	v_mov_b64_e32 v[16:17], v[14:15]
	s_lshl_b32 s50, s19, 3
	s_lshl_b32 s51, s19, 4
	v_mov_b32_e32 v198, 0
	v_mov_b32_e32 v197, 0xf149f2ca
	v_mov_b64_e32 v[14:15], v[12:13]
	v_mov_b64_e32 v[12:13], v[10:11]
	v_mov_b64_e32 v[10:11], v[8:9]
	v_mov_b64_e32 v[8:9], v[6:7]
	v_mov_b64_e32 v[6:7], v[4:5]
	v_mov_b64_e32 v[4:5], v[2:3]
	v_mov_b64_e32 v[2:3], v[0:1]
	s_mov_b32 s53, s36
